# diff attention pass-2 loop also on scalar-base + invariant VGPR-offset loads; cumulative with g5
# speedup vs baseline: 1.0079x; 1.0079x over previous
; DI int otid() { int t = threadIdx.x; asm volatile("" : "+v"(t)); return t; }
; DI float hsum(float v) { auto rr = __builtin_amdgcn_permlane32_swap(__float_as_uint(v), __float_as_uint(v), false, false); return __uint_as_float(rr[0]) + __uint_as_float(rr[1]); }
; #define PROW() (P + (tokbase + qs0 + (otid() >> 6) * 32 + (otid() & 31)) * PW)
; #define O1G() (PROW() + C_DQ + hq * 128)
; DI void stage_q(const u16* qptr, char* lds) {
;   const int tid = otid(), lane = tid & 63, r = lane & 31, h = lane >> 5;
;   char* qlds = lds + 49152 + (tid >> 6) * 4096;
;   bf16x8 q[4];
; #pragma unroll
;   for (int s = 0; s < 4; ++s) q[s] = *(const bf16x8*)(qptr + 16 * s + 8 * h);
; #pragma unroll
;   for (int s = 0; s < 4; ++s) { const int ch = 2 * s + h; *(bf16x8*)(qlds + ch * 512 + ((r ^ ch) * 16)) = q[s]; }
; }
; template <int DV>
; DI void attn_core(const u16* __restrict__ P, size_t tokbase, int kcol, int vcol, int n1, int n2, int xs0,
;                   bool win, int tq, float m0, float l0, f32x16 (&o)[DV / 32], float& lsum, char* lds) {
;     ...
;   lsum = hsum(l);
; DI void attn_item(const Params& p, int layer, int kind, int b, int hq, int qs0, char* lds) {
;     ...
;       const float inv = 1.f / ls;
;       stage_q(PROW() + C_DQ + (hq * 2 + 1) * 64, lds);
; #pragma unroll
;       for (int bk = 0; bk < 4; ++bk)
; #pragma unroll
;         for (int k2 = 0; k2 < 2; ++k2)
;           store8pair(O1G() + 32 * bk + 16 * k2, h, o[bk][8 * k2] * inv, o[bk][8 * k2 + 1] * inv, o[bk][8 * k2 + 2] * inv, o[bk][8 * k2 + 3] * inv,
;                      o[bk][8 * k2 + 4] * inv, o[bk][8 * k2 + 5] * inv, o[bk][8 * k2 + 6] * inv, o[bk][8 * k2 + 7] * inv);
.LBB0_372:
	v_mov_b32_e32 v64, v190
	s_waitcnt vmcnt(5)
	v_mov_b32_e32 v66, v190
	v_ashrrev_i32_e32 v64, 1, v64
	v_and_b32_e32 v64, 0xffffffe0, v64
	v_add_u32_e32 v64, s50, v64
	v_mov_b32_e32 v86, v190
	v_and_or_b32 v64, v66, 31, v64
	v_mov_b64_e32 v[66:67], s[22:23]
	v_mad_i64_i32 v[68:69], s[0:1], v64, s89, v[66:67]
	s_lshl_b64 s[2:3], s[26:27], 1
	v_lshl_add_u64 v[68:69], v[68:69], 0, s[2:3]
	v_bfe_u32 v87, v86, 5, 1
	v_lshlrev_b32_e32 v64, 4, v87
	v_lshl_add_u64 v[68:69], v[68:69], 0, v[64:65]
	s_mov_b64 s[0:1], 0x2280
	v_lshl_add_u64 v[82:83], v[68:69], 0, s[0:1]
	v_add_co_u32_e32 v68, vcc, s72, v68
	v_mov_b32_e32 v64, v185
	s_nop 0
	v_addc_co_u32_e32 v69, vcc, 0, v69, vcc
	global_load_dwordx4 v[70:73], v[68:69], off offset:640
	global_load_dwordx4 v[74:77], v[82:83], off offset:32
	global_load_dwordx4 v[78:81], v[82:83], off offset:64
	s_nop 0
	global_load_dwordx4 v[82:85], v[82:83], off offset:96
	v_permlane32_swap_b32_e32 v185, v64
	v_add_f32_e32 v68, v185, v64
	v_lshrrev_b32_e32 v64, 5, v86
	v_lshlrev_b32_e32 v90, 6, v86
	v_and_b32_e32 v86, 31, v86
	v_div_scale_f32 v91, s[0:1], v68, v68, 1.0
	v_lshlrev_b32_e32 v93, 9, v87
	v_bitop3_b32 v64, v64, v86, 1 bitop3:0x6c
	v_or_b32_e32 v94, 2, v87
	v_bitop3_b32 v95, v87, v86, 2 bitop3:0x36
	v_or_b32_e32 v96, 4, v87
	v_bitop3_b32 v97, v87, v86, 4 bitop3:0x36
	v_or_b32_e32 v98, 6, v87
	v_bitop3_b32 v86, v87, v86, 6 bitop3:0x36
	v_rcp_f32_e32 v87, v91
	v_and_b32_e32 v90, 0xfffff000, v90
	v_lshlrev_b32_e32 v64, 4, v64
	v_lshlrev_b32_e32 v94, 9, v94
	v_lshlrev_b32_e32 v95, 4, v95
	v_lshlrev_b32_e32 v96, 9, v96
	v_lshlrev_b32_e32 v97, 4, v97
	v_lshlrev_b32_e32 v98, 9, v98
	v_lshlrev_b32_e32 v86, 4, v86
	v_or3_b32 v93, v90, v93, v64
	v_or3_b32 v94, v90, v94, v95
	v_or3_b32 v95, v90, v96, v97
	v_or3_b32 v86, v90, v98, v86
	v_fma_f32 v90, -v91, v87, 1.0
	v_div_scale_f32 v92, vcc, 1.0, v68, 1.0
	v_fmac_f32_e32 v87, v90, v87
	v_mul_f32_e32 v90, v92, v87
	v_fma_f32 v96, -v91, v90, v92
	v_fmac_f32_e32 v90, v96, v87
	v_fma_f32 v91, -v91, v90, v92
	v_div_fmas_f32 v87, v91, v87, v90
	v_bfe_u32 v69, v146, 5, 1
	v_div_fixup_f32 v68, v87, v68, 1.0
	v_mov_b32_e32 v88, v190
	v_pk_mul_f32 v[48:49], v[48:49], v[68:69] op_sel_hi:[1,0]
	v_pk_mul_f32 v[50:51], v[50:51], v[68:69] op_sel_hi:[1,0]
	v_pk_mul_f32 v[52:53], v[52:53], v[68:69] op_sel_hi:[1,0]
	v_cvt_pk_bf16_f32 v48, v48, v49
	v_cvt_pk_bf16_f32 v49, v50, v51
	v_cvt_pk_bf16_f32 v50, v52, v53
	v_mov_b32_e32 v89, v190
	v_lshlrev_b32_e32 v64, 4, v69
	v_pk_mul_f32 v[54:55], v[54:55], v[68:69] op_sel_hi:[1,0]
	v_permlane32_swap_b32_e32 v48, v50
	v_cvt_pk_bf16_f32 v51, v54, v55
	s_nop 1
	v_permlane32_swap_b32_e32 v49, v51
	v_pk_mul_f32 v[54:55], v[60:61], v[68:69] op_sel_hi:[1,0]
	v_pk_mul_f32 v[32:33], v[32:33], v[68:69] op_sel_hi:[1,0]
	v_pk_mul_f32 v[34:35], v[34:35], v[68:69] op_sel_hi:[1,0]
	v_pk_mul_f32 v[36:37], v[36:37], v[68:69] op_sel_hi:[1,0]
	v_pk_mul_f32 v[38:39], v[38:39], v[68:69] op_sel_hi:[1,0]
	v_cvt_pk_bf16_f32 v32, v32, v33
	v_cvt_pk_bf16_f32 v33, v34, v35
	v_cvt_pk_bf16_f32 v34, v36, v37
	v_cvt_pk_bf16_f32 v35, v38, v39
	s_nop 0
	v_permlane32_swap_b32_e32 v32, v34
	s_waitcnt vmcnt(3)
	ds_write_b128 v93, v[70:73] offset:49152
	s_waitcnt vmcnt(2)
	ds_write_b128 v94, v[74:77] offset:49152
	s_waitcnt vmcnt(1)
	ds_write_b128 v95, v[78:81] offset:49152
	s_waitcnt vmcnt(0)
	ds_write_b128 v86, v[82:85] offset:49152
	v_permlane32_swap_b32_e32 v33, v35
	v_ashrrev_i32_e32 v52, 1, v88
	v_and_b32_e32 v52, 0xffffffe0, v52
	v_add_u32_e32 v52, s50, v52
	v_and_or_b32 v52, v89, 31, v52
	v_mad_i64_i32 v[52:53], s[0:1], v52, s89, v[66:67]
	v_lshl_add_u64 v[52:53], v[52:53], 0, s[2:3]
	v_lshl_add_u64 v[52:53], v[52:53], 0, v[64:65]
	v_add_co_u32_e32 v52, vcc, s72, v52
	v_pk_mul_f32 v[38:39], v[44:45], v[68:69] op_sel_hi:[1,0]
	s_nop 0
	v_addc_co_u32_e32 v53, vcc, 0, v53, vcc
	global_store_dwordx4 v[52:53], v[48:51], off offset:512
	v_pk_mul_f32 v[16:17], v[16:17], v[68:69] op_sel_hi:[1,0]
	v_pk_mul_f32 v[18:19], v[18:19], v[68:69] op_sel_hi:[1,0]
	v_mov_b32_e32 v48, v190
	v_mov_b32_e32 v49, v190
	v_ashrrev_i32_e32 v48, 1, v48
	v_and_b32_e32 v48, 0xffffffe0, v48
	v_add_u32_e32 v48, s50, v48
	v_pk_mul_f32 v[50:51], v[58:59], v[68:69] op_sel_hi:[1,0]
	v_and_or_b32 v48, v49, 31, v48
	v_mad_i64_i32 v[48:49], s[0:1], v48, s89, v[66:67]
	v_lshl_add_u64 v[52:53], v[48:49], 0, s[2:3]
	v_pk_mul_f32 v[48:49], v[56:57], v[68:69] op_sel_hi:[1,0]
	v_pk_mul_f32 v[56:57], v[62:63], v[68:69] op_sel_hi:[1,0]
	v_lshl_add_u64 v[52:53], v[52:53], 0, v[64:65]
	v_cvt_pk_bf16_f32 v48, v48, v49
	v_cvt_pk_bf16_f32 v49, v50, v51
	v_cvt_pk_bf16_f32 v50, v54, v55
	v_cvt_pk_bf16_f32 v51, v56, v57
	v_add_co_u32_e32 v52, vcc, s72, v52
	v_permlane32_swap_b32_e32 v48, v50
	v_permlane32_swap_b32_e32 v49, v51
	v_addc_co_u32_e32 v53, vcc, 0, v53, vcc
	global_store_dwordx4 v[52:53], v[48:51], off offset:544
	v_pk_mul_f32 v[20:21], v[20:21], v[68:69] op_sel_hi:[1,0]
	v_pk_mul_f32 v[22:23], v[22:23], v[68:69] op_sel_hi:[1,0]
	v_mov_b32_e32 v48, v190
	v_mov_b32_e32 v49, v190
	v_ashrrev_i32_e32 v48, 1, v48
	v_and_b32_e32 v48, 0xffffffe0, v48
	v_add_u32_e32 v48, s50, v48
	v_cvt_pk_bf16_f32 v16, v16, v17
	v_and_or_b32 v48, v49, 31, v48
	v_mad_i64_i32 v[48:49], s[0:1], v48, s89, v[66:67]
	v_lshl_add_u64 v[48:49], v[48:49], 0, s[2:3]
	v_lshl_add_u64 v[36:37], v[48:49], 0, v[64:65]
	v_add_co_u32_e32 v36, vcc, s72, v36
	v_cvt_pk_bf16_f32 v17, v18, v19
	s_nop 0
	v_addc_co_u32_e32 v37, vcc, 0, v37, vcc
	global_store_dwordx4 v[36:37], v[32:35], off offset:576
	v_cvt_pk_bf16_f32 v18, v20, v21
	v_cvt_pk_bf16_f32 v19, v22, v23
	v_mov_b32_e32 v32, v190
	v_mov_b32_e32 v33, v190
	v_ashrrev_i32_e32 v32, 1, v32
; DI int otid() { int t = threadIdx.x; asm volatile("" : "+v"(t)); return t; }
; DI f32x16 fzero() { f32x16 z; for (int i = 0; i < 16; ++i) z[i] = 0.f; return z; }
; #define O1G() (PROW() + C_DQ + hq * 128)
; template <int DV>
; DI void attn_core(const u16* __restrict__ P, size_t tokbase, int kcol, int vcol, int n1, int n2, int xs0,
;                   bool win, int tq, float m0, float l0, f32x16 (&o)[DV / 32], float& lsum, char* lds) {
;     ...
;   const int tid = otid(), lane = tid & 63, r = lane & 31, h = lane >> 5;
;   const char* qlds = lds + 49152 + (tid >> 6) * 4096;
;   bf16x8 qreg[4];
; #pragma unroll
;   for (int s = 0; s < 4; ++s) { const int ch = 2 * s + h; qreg[s] = *(const bf16x8*)(qlds + ch * 512 + ((r ^ ch) * 16)); }
;   u32x4 kA[2], vA[NVL], kB[2], vB[NVL];
;   const int ntiles = n1 + n2;
;   const int kkey = tid >> 3, kch = tid & 7;
;   const int vkey = tid >> VSH, vpc = tid & ((1 << VSH) - 1);
;   const int vstep = 256 >> VSH;
;   const bool autoinit = (l0 == 0.f);
;   float m = autoinit ? 0.f : m0, l = (h == 0) ? l0 : 0.f;
;   f32x16 negm;
; #pragma unroll
;   for (int reg = 0; reg < 16; ++reg) negm[reg] = -m;
; #pragma unroll
;   for (int b = 0; b < DV / 32; ++b) o[b] = fzero();
;   const int trofs = (4 * h + ((lane & 15) >> 2)) * 64 + ((lane >> 4) & 1) * 32 + (lane & 3) * 8;
; DI void attn_item(const Params& p, int layer, int kind, int b, int hq, int qs0, char* lds) {
;     ...
;           store8pair(O1G() + 32 * bk + 16 * k2, h, o[bk][8 * k2] * inv, o[bk][8 * k2 + 1] * inv, o[bk][8 * k2 + 2] * inv, o[bk][8 * k2 + 3] * inv,
;                      o[bk][8 * k2 + 4] * inv, o[bk][8 * k2 + 5] * inv, o[bk][8 * k2 + 6] * inv, o[bk][8 * k2 + 7] * inv);
;     }
;     f32x16 o[4]; float ls;
;     attn_core<128>(P, tokbase, C_DK + (hk * 2 + 1) * 64, C_DV + hk * 128, n1, 0, 0, false, 0, -1e30f, 0.f, o, ls, lds);
	v_and_b32_e32 v32, 0xffffffe0, v32
	v_add_u32_e32 v32, s50, v32
	v_pk_mul_f32 v[34:35], v[42:43], v[68:69] op_sel_hi:[1,0]
	v_and_or_b32 v32, v33, 31, v32
	v_mad_i64_i32 v[32:33], s[0:1], v32, s89, v[66:67]
	v_lshl_add_u64 v[36:37], v[32:33], 0, s[2:3]
	v_pk_mul_f32 v[32:33], v[40:41], v[68:69] op_sel_hi:[1,0]
	v_pk_mul_f32 v[40:41], v[46:47], v[68:69] op_sel_hi:[1,0]
	v_lshl_add_u64 v[36:37], v[36:37], 0, v[64:65]
	v_cvt_pk_bf16_f32 v32, v32, v33
	v_cvt_pk_bf16_f32 v33, v34, v35
	v_cvt_pk_bf16_f32 v34, v38, v39
	v_cvt_pk_bf16_f32 v35, v40, v41
	v_add_co_u32_e32 v36, vcc, s72, v36
	v_permlane32_swap_b32_e32 v32, v34
	v_permlane32_swap_b32_e32 v33, v35
	v_addc_co_u32_e32 v37, vcc, 0, v37, vcc
	global_store_dwordx4 v[36:37], v[32:35], off offset:608
	v_permlane32_swap_b32_e32 v16, v18
	s_nop 0
	v_mov_b32_e32 v32, v190
	v_mov_b32_e32 v33, v190
	v_ashrrev_i32_e32 v32, 1, v32
	v_and_b32_e32 v32, 0xffffffe0, v32
	v_add_u32_e32 v32, s50, v32
	v_permlane32_swap_b32_e32 v17, v19
	v_and_or_b32 v32, v33, 31, v32
	v_mad_i64_i32 v[32:33], s[0:1], v32, s89, v[66:67]
	v_lshl_add_u64 v[32:33], v[32:33], 0, s[2:3]
	v_lshl_add_u64 v[20:21], v[32:33], 0, v[64:65]
	v_add_co_u32_e32 v20, vcc, s72, v20
	v_pk_mul_f32 v[22:23], v[28:29], v[68:69] op_sel_hi:[1,0]
	s_nop 0
	v_addc_co_u32_e32 v21, vcc, 0, v21, vcc
	global_store_dwordx4 v[20:21], v[16:19], off offset:640
	v_pk_mul_f32 v[0:1], v[0:1], v[68:69] op_sel_hi:[1,0]
	v_pk_mul_f32 v[2:3], v[2:3], v[68:69] op_sel_hi:[1,0]
	v_mov_b32_e32 v16, v190
	v_mov_b32_e32 v17, v190
	v_ashrrev_i32_e32 v16, 1, v16
	v_and_b32_e32 v16, 0xffffffe0, v16
	v_add_u32_e32 v16, s50, v16
	v_pk_mul_f32 v[18:19], v[26:27], v[68:69] op_sel_hi:[1,0]
	v_and_or_b32 v16, v17, 31, v16
	v_mad_i64_i32 v[16:17], s[0:1], v16, s89, v[66:67]
	v_lshl_add_u64 v[20:21], v[16:17], 0, s[2:3]
	v_pk_mul_f32 v[16:17], v[24:25], v[68:69] op_sel_hi:[1,0]
	v_pk_mul_f32 v[24:25], v[30:31], v[68:69] op_sel_hi:[1,0]
	v_lshl_add_u64 v[20:21], v[20:21], 0, v[64:65]
	v_cvt_pk_bf16_f32 v16, v16, v17
	v_cvt_pk_bf16_f32 v17, v18, v19
	v_cvt_pk_bf16_f32 v18, v22, v23
	v_cvt_pk_bf16_f32 v19, v24, v25
	v_add_co_u32_e32 v20, vcc, s72, v20
	v_permlane32_swap_b32_e32 v16, v18
	v_permlane32_swap_b32_e32 v17, v19
	v_addc_co_u32_e32 v21, vcc, 0, v21, vcc
	global_store_dwordx4 v[20:21], v[16:19], off offset:672
	v_pk_mul_f32 v[4:5], v[4:5], v[68:69] op_sel_hi:[1,0]
	v_pk_mul_f32 v[6:7], v[6:7], v[68:69] op_sel_hi:[1,0]
	v_mov_b32_e32 v16, v190
	v_mov_b32_e32 v17, v190
	v_ashrrev_i32_e32 v16, 1, v16
	v_and_b32_e32 v16, 0xffffffe0, v16
	v_add_u32_e32 v16, s50, v16
	v_cvt_pk_bf16_f32 v0, v0, v1
	v_and_or_b32 v16, v17, 31, v16
	v_mad_i64_i32 v[16:17], s[0:1], v16, s89, v[66:67]
	v_lshl_add_u64 v[16:17], v[16:17], 0, s[2:3]
	v_cvt_pk_bf16_f32 v1, v2, v3
	v_cvt_pk_bf16_f32 v2, v4, v5
	v_lshl_add_u64 v[4:5], v[16:17], 0, v[64:65]
	v_cvt_pk_bf16_f32 v3, v6, v7
	v_add_co_u32_e32 v4, vcc, s72, v4
	v_permlane32_swap_b32_e32 v0, v2
	v_permlane32_swap_b32_e32 v1, v3
	v_addc_co_u32_e32 v5, vcc, 0, v5, vcc
	global_store_dwordx4 v[4:5], v[0:3], off offset:704
	v_pk_mul_f32 v[6:7], v[12:13], v[68:69] op_sel_hi:[1,0]
	v_mov_b32_e32 v28, v190
	v_mov_b32_e32 v0, v190
	v_mov_b32_e32 v1, v190
	v_ashrrev_i32_e32 v0, 1, v0
	v_and_b32_e32 v0, 0xffffffe0, v0
	v_add_u32_e32 v0, s50, v0
	v_pk_mul_f32 v[2:3], v[10:11], v[68:69] op_sel_hi:[1,0]
	v_and_or_b32 v0, v1, 31, v0
	v_mad_i64_i32 v[0:1], s[0:1], v0, s89, v[66:67]
	v_lshl_add_u64 v[4:5], v[0:1], 0, s[2:3]
	v_pk_mul_f32 v[0:1], v[8:9], v[68:69] op_sel_hi:[1,0]
	v_pk_mul_f32 v[8:9], v[14:15], v[68:69] op_sel_hi:[1,0]
	v_lshl_add_u64 v[4:5], v[4:5], 0, v[64:65]
	v_cvt_pk_bf16_f32 v0, v0, v1
	v_cvt_pk_bf16_f32 v1, v2, v3
	v_cvt_pk_bf16_f32 v2, v6, v7
	v_cvt_pk_bf16_f32 v3, v8, v9
	v_add_co_u32_e32 v4, vcc, s72, v4
	s_lshl_b32 s0, s51, 1
	v_permlane32_swap_b32_e32 v0, v2
	v_permlane32_swap_b32_e32 v1, v3
	v_addc_co_u32_e32 v5, vcc, 0, v5, vcc
	s_or_b32 s36, s0, 0x2680
	global_store_dwordx4 v[4:5], v[0:3], off offset:736
	s_add_u32 s0, s62, s36
	v_and_b32_e32 v31, 7, v28
	v_ashrrev_i32_e32 v29, 3, v28
	s_addc_u32 s1, s63, 0
	v_lshlrev_b32_e32 v24, 4, v31
	v_mov_b32_e32 v25, v65
	v_lshl_add_u64 v[0:1], s[0:1], 0, v[24:25]
	v_add_u32_e32 v32, 32, v29
	v_mad_i64_i32 v[2:3], s[0:1], v29, s89, v[0:1]
	v_mad_i64_i32 v[4:5], s[0:1], v32, s89, v[0:1]
	global_load_dwordx4 v[0:3], v[2:3], off
	s_nop 0
	global_load_dwordx4 v[4:7], v[4:5], off
	v_and_b32_e32 v8, 15, v28
	v_ashrrev_i32_e32 v30, 4, v28
	v_lshlrev_b32_e32 v26, 4, v8
	v_mov_b32_e32 v27, v65
	v_lshl_add_u64 v[16:17], s[30:31], 0, v[26:27]
	v_add_u32_e32 v10, 16, v30
	v_add_u32_e32 v18, 32, v30
	v_add_u32_e32 v20, 48, v30
	v_mad_i64_i32 v[8:9], s[0:1], v30, s89, v[16:17]
	v_mad_i64_i32 v[12:13], s[0:1], v10, s89, v[16:17]
	v_mad_i64_i32 v[18:19], s[0:1], v18, s89, v[16:17]
	v_mad_i64_i32 v[20:21], s[0:1], v20, s89, v[16:17]
	global_load_dwordx4 v[8:11], v[8:9], off
	s_nop 0
	global_load_dwordx4 v[12:15], v[12:13], off
	s_nop 0
	global_load_dwordx4 v[16:19], v[18:19], off
	s_nop 0
	global_load_dwordx4 v[20:23], v[20:21], off
	v_and_b32_e32 v33, 31, v28
	v_lshrrev_b32_e32 v34, 5, v28
	v_bfe_u32 v35, v28, 5, 1
	v_lshlrev_b32_e32 v36, 6, v28
	v_bitop3_b32 v34, v34, v33, 1 bitop3:0x6c
	v_and_b32_e32 v36, 0xfffff000, v36
	v_lshlrev_b32_e32 v37, 9, v35
	v_lshlrev_b32_e32 v139, 4, v34
	v_or3_b32 v34, v36, v37, v139
	v_or_b32_e32 v37, 2, v35
	v_bitop3_b32 v39, v35, v33, 2 bitop3:0x36
	v_lshlrev_b32_e32 v38, 9, v37
	v_lshlrev_b32_e32 v150, 4, v39
	v_or3_b32 v38, v36, v38, v150
	ds_read_b128 v[98:101], v34 offset:49152
	ds_read_b128 v[102:105], v38 offset:49152
	v_or_b32_e32 v34, 4, v35
	v_bitop3_b32 v39, v35, v33, 4 bitop3:0x36
	v_bitop3_b32 v42, v29, v28, 7 bitop3:0x78
	v_lshlrev_b32_e32 v38, 9, v34
	v_lshlrev_b32_e32 v151, 4, v39
	v_or_b32_e32 v39, 6, v35
	v_bitop3_b32 v41, v35, v33, 6 bitop3:0x36
	v_lshlrev_b32_e32 v31, 10, v31
	v_lshlrev_b32_e32 v42, 4, v42
	v_or3_b32 v38, v36, v38, v151
	v_lshlrev_b32_e32 v40, 9, v39
	v_lshlrev_b32_e32 v152, 4, v41
	v_add_u32_e32 v153, v31, v42
	v_or3_b32 v36, v36, v40, v152
	ds_read_b128 v[106:109], v38 offset:49152
	ds_read_b128 v[110:113], v36 offset:49152
	v_lshlrev_b32_e32 v36, 4, v28
	v_and_b32_e32 v156, 48, v36
	v_and_b32_e32 v38, 0xc0, v36
	v_lshlrev_b32_e32 v40, 1, v28
	v_lshlrev_b32_e32 v41, 3, v28
	v_and_b32_e32 v40, 32, v40
	v_and_b32_e32 v41, 24, v41
	v_lshl_or_b32 v38, v35, 8, v38
	v_lshlrev_b32_e32 v158, 10, v35
	v_lshlrev_b32_e32 v159, 10, v37
	v_lshlrev_b32_e32 v160, 10, v34
	v_lshlrev_b32_e32 v161, 10, v39
	v_or3_b32 v157, v38, v40, v41
	v_bfrev_b32_e32 v66, 1
	s_mov_b32 s26, 0
	v_lshlrev_b32_e32 v138, 3, v69
	v_mov_b32_e32 v186, 0
	v_mov_b32_e32 v166, 0
	v_mov_b32_e32 v67, v66
	v_mov_b32_e32 v68, v66
	v_mov_b32_e32 v69, v66
	v_mov_b32_e32 v70, v66
	v_mov_b32_e32 v71, v66
	v_mov_b32_e32 v72, v66
	v_mov_b32_e32 v73, v66
	v_mov_b32_e32 v74, v66
	v_mov_b32_e32 v75, v66
	v_mov_b32_e32 v76, v66
	v_mov_b32_e32 v77, v66
	v_mov_b32_e32 v78, v66
	s_waitcnt vmcnt(5)
; DI f32x16 fzero() { f32x16 z; for (int i = 0; i < 16; ++i) z[i] = 0.f; return z; }
; template <int DV>
; DI void attn_core(const u16* __restrict__ P, size_t tokbase, int kcol, int vcol, int n1, int n2, int xs0,
;                   bool win, int tq, float m0, float l0, f32x16 (&o)[DV / 32], float& lsum, char* lds) {
;     ...
;   float m = autoinit ? 0.f : m0, l = (h == 0) ? l0 : 0.f;
;   f32x16 negm;
; #pragma unroll
;   for (int reg = 0; reg < 16; ++reg) negm[reg] = -m;
; #pragma unroll
;   for (int b = 0; b < DV / 32; ++b) o[b] = fzero();
;   const int trofs = (4 * h + ((lane & 15) >> 2)) * 64 + ((lane >> 4) & 1) * 32 + (lane & 3) * 8;
;     ...
;     A_LOAD(kA, vA, 0);
;     A_STORE(kA, vA, 0);
;     __syncthreads();
	ds_write_b128 v153, v[0:3]
	v_bitop3_b32 v0, v32, v28, 7 bitop3:0x78
	v_lshlrev_b32_e32 v0, 4, v0
	v_add_u32_e32 v154, v31, v0
	v_lshlrev_b32_e32 v0, 10, v28
	v_and_b32_e32 v0, 0x3000, v0
	v_lshl_add_u32 v155, v30, 6, v0
	v_or_b32_e32 v0, v155, v156
	s_waitcnt vmcnt(4)
	ds_write_b128 v154, v[4:7]
	s_waitcnt vmcnt(3)
	ds_write_b128 v0, v[8:11] offset:8192
	s_waitcnt vmcnt(2)
	ds_write_b128 v0, v[12:15] offset:9216
	s_waitcnt vmcnt(1)
	ds_write_b128 v0, v[16:19] offset:10240
	s_waitcnt vmcnt(0)
	ds_write_b128 v0, v[20:23] offset:11264
	v_or_b32_e32 v0, 32, v33
	v_bitop3_b32 v1, v33, v35, 32 bitop3:0x36
	v_lshlrev_b32_e32 v16, 4, v1
	v_bitop3_b32 v1, v35, v0, 2 bitop3:0x36
	v_lshlrev_b32_e32 v17, 4, v1
	v_bitop3_b32 v1, v35, v0, 4 bitop3:0x36
	v_bitop3_b32 v0, v35, v0, 6 bitop3:0x36
	v_lshlrev_b32_e32 v18, 4, v1
	v_lshlrev_b32_e32 v19, 4, v0
	v_mad_i64_i32 v[0:1], s[0:1], v29, s89, v[24:25]
	s_add_u32 s0, s48, s36
	s_addc_u32 s1, s49, 0
	v_lshl_add_u64 v[140:141], s[0:1], 0, v[0:1]
	v_mov_b64_e32 v[0:1], s[28:29]
	v_mad_i64_i32 v[0:1], s[0:1], v30, s89, v[0:1]
	v_lshl_add_u64 v[0:1], v[0:1], 0, v[26:27]
	v_mov_b32_e32 v14, v65
	v_mov_b32_e32 v15, v65
	v_lshl_add_u64 v[142:143], s[48:49], 0, v[0:1]
	s_sub_u32 s92, s48, 0x100000
	s_subb_u32 s93, s49, 0
	v_subrev_u32_e32 v176, s92, v140
	v_subrev_u32_e32 v178, s92, v142
	v_add_u32_e32 v177, 0x115800, v176
	v_add_u32_e32 v176, 0xb9000, v176
	v_add_u32_e32 v179, 0xe9c00, v178
	v_add_u32_e32 v180, 0x118000, v178
	v_add_u32_e32 v181, 0x146400, v178
	v_add_u32_e32 v178, 0xbb800, v178
	v_mov_b32_e32 v0, v65
	v_mov_b32_e32 v1, v65
	v_mov_b32_e32 v2, v65
	v_mov_b32_e32 v3, v65
	v_mov_b32_e32 v4, v65
	v_mov_b32_e32 v5, v65
	v_mov_b32_e32 v6, v65
	v_mov_b32_e32 v7, v65
	v_mov_b32_e32 v8, v65
	v_mov_b32_e32 v9, v65
	v_mov_b32_e32 v10, v65
	v_mov_b32_e32 v11, v65
	v_mov_b32_e32 v12, v65
	v_mov_b32_e32 v13, v65
	v_add_u32_e32 v162, v158, v16
	v_add_u32_e32 v163, v159, v17
	v_add_u32_e32 v164, v160, v18
	v_add_u32_e32 v165, v161, v19
	v_mov_b64_e32 v[30:31], v[14:15]
	v_mov_b64_e32 v[46:47], v[14:15]
	v_mov_b64_e32 v[62:63], v[14:15]
	s_mov_b64 s[28:29], 0
	v_mov_b64_e32 v[28:29], v[12:13]
	v_mov_b64_e32 v[26:27], v[10:11]
	v_mov_b64_e32 v[24:25], v[8:9]
	v_mov_b64_e32 v[22:23], v[6:7]
	v_mov_b64_e32 v[20:21], v[4:5]
	v_mov_b64_e32 v[18:19], v[2:3]
	v_mov_b64_e32 v[16:17], v[0:1]
	v_mov_b64_e32 v[44:45], v[12:13]
	v_mov_b64_e32 v[42:43], v[10:11]
	v_mov_b64_e32 v[40:41], v[8:9]
	v_mov_b64_e32 v[38:39], v[6:7]
	v_mov_b64_e32 v[36:37], v[4:5]
	v_mov_b64_e32 v[34:35], v[2:3]
	v_mov_b64_e32 v[32:33], v[0:1]
	v_mov_b64_e32 v[60:61], v[12:13]
	v_mov_b64_e32 v[58:59], v[10:11]
	v_mov_b64_e32 v[56:57], v[8:9]
	v_mov_b64_e32 v[54:55], v[6:7]
	v_mov_b64_e32 v[52:53], v[4:5]
	v_mov_b64_e32 v[50:51], v[2:3]
	v_mov_b64_e32 v[48:49], v[0:1]
	v_mov_b32_e32 v79, v66
	v_mov_b32_e32 v80, v66
	v_mov_b32_e32 v81, v66
	s_waitcnt lgkmcnt(0)
	s_barrier
	s_branch .LBB0_374

; #define MFMA(a, b, c) __builtin_amdgcn_mfma_f32_32x32x16_bf16((a), (b), (c), 0, 0, 0)
; DI int crow(int reg, int h) { return (reg & 3) + 8 * (reg >> 2) + 4 * h; }
; DI float mx2(float a, float b) { return __builtin_elementwise_maximum(a, b); }
; DI float hmax(float v) { auto rr = __builtin_amdgcn_permlane32_swap(__float_as_uint(v), __float_as_uint(v), false, false); return mx2(__uint_as_float(rr[0]), __uint_as_float(rr[1])); }
; template <int DV>
; DI void attn_core(const u16* __restrict__ P, size_t tokbase, int kcol, int vcol, int n1, int n2, int xs0,
;                   bool win, int tq, float m0, float l0, f32x16 (&o)[DV / 32], float& lsum, char* lds) {
;     ...
;     for (int ks = 0; ks < 2; ++ks) {
;       f32x16 pt = negm;
; #pragma unroll
;       for (int s = 0; s < 4; ++s) {
;         const int ch = 2 * s + h, key = 32 * ks + r;
;         const bf16x8 kf = *(const bf16x8*)(base + ch * 1024 + ((key ^ ch) * 16));
;         const bf16x8 qf = qreg[s];
;         pt = MFMA(kf, qf, pt);
;       }
;       if (domask) {
; #pragma unroll
;         for (int reg = 0; reg < 16; ++reg) {
;           const int d = tq - (kt0 + 32 * ks + crow(reg, h));
;           if (d > 128 || d < -128) pt[reg] = -1e30f;
;         }
;       }
;       float mloc = mx2(pt[0], pt[1]);
; #pragma unroll
;       for (int reg = 2; reg < 16; reg += 2) mloc = mx2(mx2(mloc, pt[reg]), pt[reg + 1]);
;       mloc = hmax(mloc);
;       const bool first = autoinit && it == 0 && ks == 0;
;       if (first || __builtin_amdgcn_ballot_w64(mloc > THR) != 0) {
;     ...
;     for (int it = 0; it < ntiles; it += 2) {
;       A_LOAD(kA, vA, it + 1);
;       compute(lds, it);
.LBB0_374:
	s_add_u32 s94, s92, s28
	s_addc_u32 s95, s93, s29
	s_mov_b32 s0, 0x115000
	global_load_dwordx4 v[114:117], v176, s[94:95]
	global_load_dwordx4 v[118:121], v177, s[94:95]
	v_add_u32_e32 v168, v158, v139
	global_load_dwordx4 v[122:125], v178, s[94:95]
	ds_read_b128 v[170:173], v168
	global_load_dwordx4 v[126:129], v179, s[94:95]
	v_add_u32_e32 v174, v159, v150
	global_load_dwordx4 v[130:133], v180, s[94:95]
	v_add_u32_e32 v182, v160, v151
	global_load_dwordx4 v[134:137], v181, s[94:95]
	s_waitcnt lgkmcnt(0)
	v_mfma_f32_32x32x16_bf16 v[82:97], v[170:173], v[98:101], v[66:81]
	ds_read_b128 v[170:173], v174
	v_add_u32_e32 v185, v161, v152
	s_cmp_lg_u32 s28, 0
	s_waitcnt lgkmcnt(0)
	v_mfma_f32_32x32x16_bf16 v[82:97], v[170:173], v[102:105], v[82:97]
	ds_read_b128 v[170:173], v182
	s_waitcnt lgkmcnt(0)
	v_mfma_f32_32x32x16_bf16 v[82:97], v[170:173], v[106:109], v[82:97]
	ds_read_b128 v[170:173], v185
	s_waitcnt lgkmcnt(0)
	v_mfma_f32_32x32x16_bf16 v[82:97], v[170:173], v[110:113], v[82:97]
	s_nop 11
	v_maximum3_f32 v148, v82, v83, v83
	v_maximum3_f32 v148, v148, v84, v85
	v_maximum3_f32 v148, v148, v86, v87
	v_maximum3_f32 v148, v148, v88, v89
	v_maximum3_f32 v148, v148, v90, v91
	v_maximum3_f32 v148, v148, v92, v93
	v_maximum3_f32 v148, v148, v94, v95
	v_maximum3_f32 v148, v148, v96, v97
	v_mov_b32_e32 v167, v148
	s_nop 1
	v_permlane32_swap_b32_e32 v148, v167
	v_maximum3_f32 v167, v148, v167, v167
	s_cbranch_scc0 .LBB0_390
	v_cmp_lt_f32_e32 vcc, s80, v167
	s_mov_b64 s[30:31], 0
	s_mov_b64 s[0:1], 0
	s_cbranch_vccz .LBB0_377
	v_max_f32_e32 v148, v167, v167
	v_max_f32_e32 v148, 0, v148
	s_mov_b64 s[0:1], -1

; #define MFMA(a, b, c) __builtin_amdgcn_mfma_f32_32x32x16_bf16((a), (b), (c), 0, 0, 0)
; DI int crow(int reg, int h) { return (reg & 3) + 8 * (reg >> 2) + 4 * h; }
; DI s16x4 vtr(const char* p) { return __builtin_bit_cast(s16x4, __builtin_amdgcn_ds_read_tr16_b64_v4i16((__attribute__((address_space(3))) v4i16_t*)(lds_cptr)p)); }
; template <int DV>
; DI void attn_core(const u16* __restrict__ P, size_t tokbase, int kcol, int vcol, int n1, int n2, int xs0,
;                   bool win, int tq, float m0, float l0, f32x16 (&o)[DV / 32], float& lsum, char* lds) {
;     ...
;     for (int ks = 0; ks < 2; ++ks) {
;       f32x16 pt = negm;
; #pragma unroll
;       for (int s = 0; s < 4; ++s) {
;         const int ch = 2 * s + h, key = 32 * ks + r;
;         const bf16x8 kf = *(const bf16x8*)(base + ch * 1024 + ((key ^ ch) * 16));
;         const bf16x8 qf = qreg[s];
;         pt = MFMA(kf, qf, pt);
;       }
;       if (domask) {
; #pragma unroll
;         for (int reg = 0; reg < 16; ++reg) {
;           const int d = tq - (kt0 + 32 * ks + crow(reg, h));
;           if (d > 128 || d < -128) pt[reg] = -1e30f;
;         }
;       }
;       float mloc = mx2(pt[0], pt[1]);
; #pragma unroll
;       for (int reg = 2; reg < 16; reg += 2) mloc = mx2(mx2(mloc, pt[reg]), pt[reg + 1]);
;       mloc = hmax(mloc);
;       const bool first = autoinit && it == 0 && ks == 0;
;       if (first || __builtin_amdgcn_ballot_w64(mloc > THR) != 0) {
;         const float d = first ? mloc : fmaxf(mloc, 0.f);
;         const float alpha = fexp2(-d);
;         m += d; l *= alpha;
; #pragma unroll
;         for (int reg = 0; reg < 16; ++reg) { negm[reg] = -m; pt[reg] -= d; }
; #pragma unroll
;         for (int b = 0; b < DV / 32; ++b)
; #pragma unroll
;           for (int reg = 0; reg < 16; ++reg) o[b][reg] *= alpha;
;       }
;       float la = 0.f;
; #pragma unroll
;       for (int reg = 0; reg < 16; ++reg) { const float e = fexp2(pt[reg]); pt[reg] = e; la += e; }
;       l += la;
; #pragma unroll
;       for (int s2 = 0; s2 < 2; ++s2) {
;         const bf16x8 pb = pack8(pt, s2);
;         const int s16 = 2 * ks + s2;
; #pragma unroll
;         for (int b = 0; b < DV / 32; ++b) {
;           const char* va = base + KB + b * 4096 + s16 * 1024 + trofs;
;           const bf16x8 vf = cat8(vtr(va), vtr(va + 512));
;           o[b] = MFMA(vf, pb, o[b]);
;         }
;       }
.LBB0_379:
	s_andn2_b64 vcc, exec, s[0:1]
	s_cbranch_vccnz .LBB0_381
	v_exp_f32_e64 v68, -v148
	v_add_f32_e32 v166, v166, v148
	v_xor_b32_e32 v66, 0x80000000, v166
	v_pk_add_f32 v[82:83], v[82:83], v[148:149] op_sel_hi:[1,0] neg_lo:[0,1] neg_hi:[0,1]
	v_mul_f32_e32 v186, v186, v68
	v_pk_add_f32 v[84:85], v[84:85], v[148:149] op_sel_hi:[1,0] neg_lo:[0,1] neg_hi:[0,1]
	v_pk_add_f32 v[86:87], v[86:87], v[148:149] op_sel_hi:[1,0] neg_lo:[0,1] neg_hi:[0,1]
	v_pk_add_f32 v[88:89], v[88:89], v[148:149] op_sel_hi:[1,0] neg_lo:[0,1] neg_hi:[0,1]
	v_pk_add_f32 v[90:91], v[90:91], v[148:149] op_sel_hi:[1,0] neg_lo:[0,1] neg_hi:[0,1]
	v_pk_add_f32 v[92:93], v[92:93], v[148:149] op_sel_hi:[1,0] neg_lo:[0,1] neg_hi:[0,1]
	v_pk_add_f32 v[94:95], v[94:95], v[148:149] op_sel_hi:[1,0] neg_lo:[0,1] neg_hi:[0,1]
	v_pk_add_f32 v[96:97], v[96:97], v[148:149] op_sel_hi:[1,0] neg_lo:[0,1] neg_hi:[0,1]
	v_pk_mul_f32 v[62:63], v[62:63], v[68:69] op_sel_hi:[1,0]
	v_pk_mul_f32 v[60:61], v[60:61], v[68:69] op_sel_hi:[1,0]
	v_pk_mul_f32 v[58:59], v[58:59], v[68:69] op_sel_hi:[1,0]
	v_pk_mul_f32 v[56:57], v[56:57], v[68:69] op_sel_hi:[1,0]
	v_pk_mul_f32 v[54:55], v[54:55], v[68:69] op_sel_hi:[1,0]
	v_pk_mul_f32 v[52:53], v[52:53], v[68:69] op_sel_hi:[1,0]
	v_pk_mul_f32 v[50:51], v[50:51], v[68:69] op_sel_hi:[1,0]
	v_pk_mul_f32 v[48:49], v[48:49], v[68:69] op_sel_hi:[1,0]
	v_pk_mul_f32 v[46:47], v[46:47], v[68:69] op_sel_hi:[1,0]
	v_pk_mul_f32 v[44:45], v[44:45], v[68:69] op_sel_hi:[1,0]
	v_pk_mul_f32 v[42:43], v[42:43], v[68:69] op_sel_hi:[1,0]
	v_pk_mul_f32 v[40:41], v[40:41], v[68:69] op_sel_hi:[1,0]
	v_pk_mul_f32 v[38:39], v[38:39], v[68:69] op_sel_hi:[1,0]
	v_pk_mul_f32 v[36:37], v[36:37], v[68:69] op_sel_hi:[1,0]
	v_pk_mul_f32 v[34:35], v[34:35], v[68:69] op_sel_hi:[1,0]
	v_pk_mul_f32 v[32:33], v[32:33], v[68:69] op_sel_hi:[1,0]
	v_pk_mul_f32 v[30:31], v[30:31], v[68:69] op_sel_hi:[1,0]
	v_pk_mul_f32 v[28:29], v[28:29], v[68:69] op_sel_hi:[1,0]
	v_pk_mul_f32 v[26:27], v[26:27], v[68:69] op_sel_hi:[1,0]
	v_pk_mul_f32 v[24:25], v[24:25], v[68:69] op_sel_hi:[1,0]
	v_pk_mul_f32 v[22:23], v[22:23], v[68:69] op_sel_hi:[1,0]
	v_pk_mul_f32 v[20:21], v[20:21], v[68:69] op_sel_hi:[1,0]
	v_pk_mul_f32 v[18:19], v[18:19], v[68:69] op_sel_hi:[1,0]
	v_pk_mul_f32 v[16:17], v[16:17], v[68:69] op_sel_hi:[1,0]
	v_pk_mul_f32 v[14:15], v[14:15], v[68:69] op_sel_hi:[1,0]
	v_pk_mul_f32 v[12:13], v[12:13], v[68:69] op_sel_hi:[1,0]
	v_pk_mul_f32 v[10:11], v[10:11], v[68:69] op_sel_hi:[1,0]
	v_pk_mul_f32 v[8:9], v[8:9], v[68:69] op_sel_hi:[1,0]
	v_pk_mul_f32 v[6:7], v[6:7], v[68:69] op_sel_hi:[1,0]
	v_pk_mul_f32 v[4:5], v[4:5], v[68:69] op_sel_hi:[1,0]
	v_pk_mul_f32 v[2:3], v[2:3], v[68:69] op_sel_hi:[1,0]
	v_pk_mul_f32 v[0:1], v[0:1], v[68:69] op_sel_hi:[1,0]
	v_mov_b32_e32 v67, v66
	v_mov_b32_e32 v68, v66
	v_mov_b32_e32 v69, v66
	v_mov_b32_e32 v70, v66
	v_mov_b32_e32 v71, v66
	v_mov_b32_e32 v72, v66
	v_mov_b32_e32 v73, v66
	v_mov_b32_e32 v74, v66
	v_mov_b32_e32 v75, v66
	v_mov_b32_e32 v76, v66
	v_mov_b32_e32 v77, v66
	v_mov_b32_e32 v78, v66
	v_mov_b32_e32 v79, v66
	v_mov_b32_e32 v80, v66
	v_mov_b32_e32 v81, v66
	v_mov_b32_e32 v148, v66
	v_mov_b32_e32 v167, v66
	v_mov_b32_e32 v169, v66
	v_mov_b32_e32 v170, v66
	v_mov_b32_e32 v171, v66
	v_mov_b32_e32 v172, v66
	v_mov_b32_e32 v173, v66
	v_mov_b32_e32 v175, v66
	v_mov_b32_e32 v183, v66
	v_mov_b32_e32 v184, v66
	s_branch .LBB0_382
.LBB0_381:
.LBB0_382:
	v_exp_f32_e32 v82, v82
	v_exp_f32_e32 v83, v83
	v_exp_f32_e32 v84, v84
	v_exp_f32_e32 v85, v85
	v_add_f32_e32 v187, 0, v82
	v_exp_f32_e32 v86, v86
	v_add_f32_e32 v187, v83, v187
	v_exp_f32_e32 v87, v87
	v_add_f32_e32 v187, v84, v187
	v_exp_f32_e32 v88, v88
	v_add_f32_e32 v187, v85, v187
	v_exp_f32_e32 v89, v89
	v_add_f32_e32 v187, v86, v187
	v_add_f32_e32 v187, v87, v187
	v_add_f32_e32 v187, v88, v187
	v_add_f32_e32 v187, v89, v187
	v_cvt_pk_bf16_f32 v82, v82, v83
	v_cvt_pk_bf16_f32 v83, v84, v85
	v_cvt_pk_bf16_f32 v84, v86, v87
	v_cvt_pk_bf16_f32 v85, v88, v89
	ds_read_b64_tr_b16 v[86:87], v157 offset:8192
	ds_read_b64_tr_b16 v[88:89], v157 offset:8704
	s_waitcnt lgkmcnt(0)
	v_mfma_f32_32x32x16_bf16 v[48:63], v[86:89], v[82:85], v[48:63]
	ds_read_b64_tr_b16 v[86:87], v157 offset:12288
	ds_read_b64_tr_b16 v[88:89], v157 offset:12800
	v_exp_f32_e32 v90, v90
	v_exp_f32_e32 v91, v91
	v_exp_f32_e32 v92, v92
	v_exp_f32_e32 v93, v93
	v_exp_f32_e32 v94, v94
	v_exp_f32_e32 v95, v95
	s_waitcnt lgkmcnt(0)
	v_mfma_f32_32x32x16_bf16 v[32:47], v[86:89], v[82:85], v[32:47]
	ds_read_b64_tr_b16 v[86:87], v157 offset:16384
	ds_read_b64_tr_b16 v[88:89], v157 offset:16896
	v_exp_f32_e32 v96, v96
	v_exp_f32_e32 v97, v97
	v_add_f32_e32 v187, v90, v187
	v_add_f32_e32 v187, v91, v187
	v_add_f32_e32 v187, v92, v187
	v_add_f32_e32 v187, v93, v187
	s_waitcnt lgkmcnt(0)
	v_mfma_f32_32x32x16_bf16 v[16:31], v[86:89], v[82:85], v[16:31]
	ds_read_b64_tr_b16 v[86:87], v157 offset:20480
	ds_read_b64_tr_b16 v[88:89], v157 offset:20992
	v_add_f32_e32 v187, v94, v187
	v_add_f32_e32 v187, v95, v187
	v_add_f32_e32 v187, v96, v187
	v_add_f32_e32 v187, v97, v187
	v_add_f32_e32 v187, v186, v187
	s_waitcnt lgkmcnt(0)
	v_mfma_f32_32x32x16_bf16 v[0:15], v[86:89], v[82:85], v[0:15]
	ds_read_b64_tr_b16 v[86:87], v157 offset:9216
	ds_read_b64_tr_b16 v[88:89], v157 offset:9728
	v_cvt_pk_bf16_f32 v82, v90, v91
	v_cvt_pk_bf16_f32 v83, v92, v93
	v_cvt_pk_bf16_f32 v84, v94, v95
	v_cvt_pk_bf16_f32 v85, v96, v97
	s_waitcnt lgkmcnt(0)
	s_nop 0
	v_mfma_f32_32x32x16_bf16 v[48:63], v[86:89], v[82:85], v[48:63]
	ds_read_b64_tr_b16 v[86:87], v157 offset:13312
	ds_read_b64_tr_b16 v[88:89], v157 offset:13824
	s_waitcnt lgkmcnt(0)
	v_mfma_f32_32x32x16_bf16 v[32:47], v[86:89], v[82:85], v[32:47]
	ds_read_b64_tr_b16 v[86:87], v157 offset:17408
	ds_read_b64_tr_b16 v[88:89], v157 offset:17920
	s_waitcnt lgkmcnt(0)
	v_mfma_f32_32x32x16_bf16 v[16:31], v[86:89], v[82:85], v[16:31]
	ds_read_b64_tr_b16 v[86:87], v157 offset:21504
	ds_read_b64_tr_b16 v[88:89], v157 offset:22016
	ds_read_b128 v[206:209], v162
	s_waitcnt lgkmcnt(1)
	v_mfma_f32_32x32x16_bf16 v[0:15], v[86:89], v[82:85], v[0:15]
	s_waitcnt lgkmcnt(0)
	v_mfma_f32_32x32x16_bf16 v[82:97], v[206:209], v[98:101], v[66:81]
	ds_read_b128 v[206:209], v163
	s_waitcnt lgkmcnt(0)
	v_mfma_f32_32x32x16_bf16 v[82:97], v[206:209], v[102:105], v[82:97]
	ds_read_b128 v[206:209], v164
	s_waitcnt lgkmcnt(0)
	v_mfma_f32_32x32x16_bf16 v[82:97], v[206:209], v[106:109], v[82:97]
	ds_read_b128 v[206:209], v165
	s_waitcnt lgkmcnt(0)
	v_mfma_f32_32x32x16_bf16 v[82:97], v[206:209], v[110:113], v[82:97]
	s_nop 11
	v_maximum3_f32 v186, v82, v83, v83
	v_maximum3_f32 v186, v186, v84, v85
	v_maximum3_f32 v186, v186, v86, v87
	v_maximum3_f32 v186, v186, v88, v89
	v_maximum3_f32 v186, v186, v90, v91
	v_maximum3_f32 v186, v186, v92, v93
	v_maximum3_f32 v186, v186, v94, v95
	v_maximum3_f32 v186, v186, v96, v97
	v_mov_b32_e32 v188, v186
	s_nop 1
	v_permlane32_swap_b32_e32 v186, v188
	v_maximum3_f32 v186, v186, v188, v188
	v_cmp_lt_f32_e32 vcc, s80, v186
	s_cbranch_vccz .LBB0_384
; #define MFMA(a, b, c) __builtin_amdgcn_mfma_f32_32x32x16_bf16((a), (b), (c), 0, 0, 0)
; DI s16x4 vtr(const char* p) { return __builtin_bit_cast(s16x4, __builtin_amdgcn_ds_read_tr16_b64_v4i16((__attribute__((address_space(3))) v4i16_t*)(lds_cptr)p)); }
; DI bf16x8 cat8(s16x4 lo, s16x4 hi) { return __builtin_shufflevector(lo, hi, 0, 1, 2, 3, 4, 5, 6, 7); }
; DI float fexp2(float x) { return __builtin_amdgcn_exp2f(x); }
; template <int DV>
; DI void attn_core(const u16* __restrict__ P, size_t tokbase, int kcol, int vcol, int n1, int n2, int xs0,
;                   bool win, int tq, float m0, float l0, f32x16 (&o)[DV / 32], float& lsum, char* lds) {
;     ...
;       if (first || __builtin_amdgcn_ballot_w64(mloc > THR) != 0) {
;         const float d = first ? mloc : fmaxf(mloc, 0.f);
;         const float alpha = fexp2(-d);
;         m += d; l *= alpha;
; #pragma unroll
;         for (int reg = 0; reg < 16; ++reg) { negm[reg] = -m; pt[reg] -= d; }
; #pragma unroll
;         for (int b = 0; b < DV / 32; ++b)
; #pragma unroll
;           for (int reg = 0; reg < 16; ++reg) o[b][reg] *= alpha;
;       }
;       float la = 0.f;
; #pragma unroll
;       for (int reg = 0; reg < 16; ++reg) { const float e = fexp2(pt[reg]); pt[reg] = e; la += e; }
;       l += la;
; #pragma unroll
;       for (int s2 = 0; s2 < 2; ++s2) {
;         const bf16x8 pb = pack8(pt, s2);
;         const int s16 = 2 * ks + s2;
; #pragma unroll
;         for (int b = 0; b < DV / 32; ++b) {
;           const char* va = base + KB + b * 4096 + s16 * 1024 + trofs;
;           const bf16x8 vf = cat8(vtr(va), vtr(va + 512));
;           o[b] = MFMA(vf, pb, o[b]);
;         }
;       }
;     ...
;       A_STORE(kA, vA, 1);
;       __syncthreads();
;       if (it + 2 < ntiles) A_LOAD(kA, vA, it + 2);
	v_max_f32_e32 v66, v186, v186
	v_max_f32_e32 v68, 0, v66
	v_exp_f32_e64 v70, -v68
	v_add_f32_e32 v166, v166, v68
	v_xor_b32_e32 v66, 0x80000000, v166
	v_pk_add_f32 v[82:83], v[82:83], v[68:69] op_sel_hi:[1,0] neg_lo:[0,1] neg_hi:[0,1]
	v_mul_f32_e32 v187, v187, v70
	v_pk_add_f32 v[84:85], v[84:85], v[68:69] op_sel_hi:[1,0] neg_lo:[0,1] neg_hi:[0,1]
	v_pk_add_f32 v[86:87], v[86:87], v[68:69] op_sel_hi:[1,0] neg_lo:[0,1] neg_hi:[0,1]
	v_pk_add_f32 v[88:89], v[88:89], v[68:69] op_sel_hi:[1,0] neg_lo:[0,1] neg_hi:[0,1]
	v_pk_add_f32 v[90:91], v[90:91], v[68:69] op_sel_hi:[1,0] neg_lo:[0,1] neg_hi:[0,1]
	v_pk_add_f32 v[92:93], v[92:93], v[68:69] op_sel_hi:[1,0] neg_lo:[0,1] neg_hi:[0,1]
	v_pk_add_f32 v[94:95], v[94:95], v[68:69] op_sel_hi:[1,0] neg_lo:[0,1] neg_hi:[0,1]
	v_pk_add_f32 v[96:97], v[96:97], v[68:69] op_sel_hi:[1,0] neg_lo:[0,1] neg_hi:[0,1]
	v_pk_mul_f32 v[62:63], v[62:63], v[70:71] op_sel_hi:[1,0]
	v_pk_mul_f32 v[60:61], v[60:61], v[70:71] op_sel_hi:[1,0]
	v_pk_mul_f32 v[58:59], v[58:59], v[70:71] op_sel_hi:[1,0]
	v_pk_mul_f32 v[56:57], v[56:57], v[70:71] op_sel_hi:[1,0]
	v_pk_mul_f32 v[54:55], v[54:55], v[70:71] op_sel_hi:[1,0]
	v_pk_mul_f32 v[52:53], v[52:53], v[70:71] op_sel_hi:[1,0]
	v_pk_mul_f32 v[50:51], v[50:51], v[70:71] op_sel_hi:[1,0]
	v_pk_mul_f32 v[48:49], v[48:49], v[70:71] op_sel_hi:[1,0]
	v_pk_mul_f32 v[46:47], v[46:47], v[70:71] op_sel_hi:[1,0]
	v_pk_mul_f32 v[44:45], v[44:45], v[70:71] op_sel_hi:[1,0]
	v_pk_mul_f32 v[42:43], v[42:43], v[70:71] op_sel_hi:[1,0]
	v_pk_mul_f32 v[40:41], v[40:41], v[70:71] op_sel_hi:[1,0]
	v_pk_mul_f32 v[38:39], v[38:39], v[70:71] op_sel_hi:[1,0]
	v_pk_mul_f32 v[36:37], v[36:37], v[70:71] op_sel_hi:[1,0]
	v_pk_mul_f32 v[34:35], v[34:35], v[70:71] op_sel_hi:[1,0]
	v_pk_mul_f32 v[32:33], v[32:33], v[70:71] op_sel_hi:[1,0]
	v_pk_mul_f32 v[30:31], v[30:31], v[70:71] op_sel_hi:[1,0]
	v_pk_mul_f32 v[28:29], v[28:29], v[70:71] op_sel_hi:[1,0]
	v_pk_mul_f32 v[26:27], v[26:27], v[70:71] op_sel_hi:[1,0]
	v_pk_mul_f32 v[24:25], v[24:25], v[70:71] op_sel_hi:[1,0]
	v_pk_mul_f32 v[22:23], v[22:23], v[70:71] op_sel_hi:[1,0]
	v_pk_mul_f32 v[20:21], v[20:21], v[70:71] op_sel_hi:[1,0]
	v_pk_mul_f32 v[18:19], v[18:19], v[70:71] op_sel_hi:[1,0]
	v_pk_mul_f32 v[16:17], v[16:17], v[70:71] op_sel_hi:[1,0]
	v_pk_mul_f32 v[14:15], v[14:15], v[70:71] op_sel_hi:[1,0]
	v_pk_mul_f32 v[12:13], v[12:13], v[70:71] op_sel_hi:[1,0]
	v_pk_mul_f32 v[10:11], v[10:11], v[70:71] op_sel_hi:[1,0]
	v_pk_mul_f32 v[8:9], v[8:9], v[70:71] op_sel_hi:[1,0]
	v_pk_mul_f32 v[6:7], v[6:7], v[70:71] op_sel_hi:[1,0]
	v_pk_mul_f32 v[4:5], v[4:5], v[70:71] op_sel_hi:[1,0]
	v_pk_mul_f32 v[2:3], v[2:3], v[70:71] op_sel_hi:[1,0]
	v_pk_mul_f32 v[0:1], v[0:1], v[70:71] op_sel_hi:[1,0]
	v_mov_b32_e32 v67, v66
	v_mov_b32_e32 v68, v66
	v_mov_b32_e32 v69, v66
	v_mov_b32_e32 v70, v66
	v_mov_b32_e32 v71, v66
	v_mov_b32_e32 v72, v66
	v_mov_b32_e32 v73, v66
	v_mov_b32_e32 v74, v66
	v_mov_b32_e32 v75, v66
	v_mov_b32_e32 v76, v66
	v_mov_b32_e32 v77, v66
	v_mov_b32_e32 v78, v66
	v_mov_b32_e32 v79, v66
	v_mov_b32_e32 v80, v66
	v_mov_b32_e32 v81, v66
	v_mov_b32_e32 v148, v66
	v_mov_b32_e32 v167, v66
	v_mov_b32_e32 v169, v66
	v_mov_b32_e32 v170, v66
	v_mov_b32_e32 v171, v66
	v_mov_b32_e32 v172, v66
	v_mov_b32_e32 v173, v66
	v_mov_b32_e32 v175, v66
	v_mov_b32_e32 v183, v66
	v_mov_b32_e32 v184, v66
.LBB0_384:
	v_exp_f32_e32 v82, v82
	v_exp_f32_e32 v83, v83
	v_exp_f32_e32 v84, v84
	v_exp_f32_e32 v85, v85
	v_exp_f32_e32 v86, v86
	v_exp_f32_e32 v87, v87
	v_exp_f32_e32 v88, v88
	v_exp_f32_e32 v89, v89
	ds_read_b64_tr_b16 v[216:217], v157 offset:10240
	ds_read_b64_tr_b16 v[218:219], v157 offset:10752
	v_cvt_pk_bf16_f32 v206, v82, v83
	v_cvt_pk_bf16_f32 v207, v84, v85
	v_cvt_pk_bf16_f32 v208, v86, v87
	v_cvt_pk_bf16_f32 v209, v88, v89
	v_exp_f32_e32 v90, v90
	v_exp_f32_e32 v91, v91
	s_waitcnt lgkmcnt(0)
	v_mfma_f32_32x32x16_bf16 v[48:63], v[216:219], v[206:209], v[48:63]
	ds_read_b64_tr_b16 v[216:217], v157 offset:14336
	ds_read_b64_tr_b16 v[218:219], v157 offset:14848
	v_exp_f32_e32 v92, v92
	v_exp_f32_e32 v93, v93
	v_exp_f32_e32 v94, v94
	v_exp_f32_e32 v95, v95
	v_exp_f32_e32 v96, v96
	v_exp_f32_e32 v97, v97
	s_waitcnt lgkmcnt(0)
	v_mfma_f32_32x32x16_bf16 v[32:47], v[216:219], v[206:209], v[32:47]
	ds_read_b64_tr_b16 v[216:217], v157 offset:18432
	ds_read_b64_tr_b16 v[218:219], v157 offset:18944
	s_cmpk_lt_u32 s26, 0x42
	s_cselect_b64 s[30:31], -1, 0
	s_cmpk_gt_u32 s26, 0x41
	s_cselect_b64 s[0:1], -1, 0
	v_add_u32_e32 v186, v155, v156
	s_and_b64 vcc, exec, s[0:1]
	s_waitcnt lgkmcnt(0)
	v_mfma_f32_32x32x16_bf16 v[16:31], v[216:219], v[206:209], v[16:31]
	ds_read_b64_tr_b16 v[216:217], v157 offset:22528
	ds_read_b64_tr_b16 v[218:219], v157 offset:23040
	s_waitcnt lgkmcnt(0)
	v_mfma_f32_32x32x16_bf16 v[0:15], v[216:219], v[206:209], v[0:15]
	ds_read_b64_tr_b16 v[216:217], v157 offset:11264
	ds_read_b64_tr_b16 v[218:219], v157 offset:11776
	v_cvt_pk_bf16_f32 v206, v90, v91
	v_cvt_pk_bf16_f32 v207, v92, v93
	v_cvt_pk_bf16_f32 v208, v94, v95
	v_cvt_pk_bf16_f32 v209, v96, v97
	s_waitcnt lgkmcnt(0)
	s_nop 0
	v_mfma_f32_32x32x16_bf16 v[48:63], v[216:219], v[206:209], v[48:63]
	ds_read_b64_tr_b16 v[216:217], v157 offset:15360
	ds_read_b64_tr_b16 v[218:219], v157 offset:15872
	s_waitcnt lgkmcnt(0)
	v_mfma_f32_32x32x16_bf16 v[32:47], v[216:219], v[206:209], v[32:47]
	ds_read_b64_tr_b16 v[216:217], v157 offset:19456
	ds_read_b64_tr_b16 v[218:219], v157 offset:19968
	s_waitcnt lgkmcnt(0)
	v_mfma_f32_32x32x16_bf16 v[16:31], v[216:219], v[206:209], v[16:31]
	ds_read_b64_tr_b16 v[216:217], v157 offset:23552
	ds_read_b64_tr_b16 v[218:219], v157 offset:24064
	s_waitcnt vmcnt(5)
	ds_write_b128 v153, v[114:117] offset:24576
	s_waitcnt vmcnt(4)
	ds_write_b128 v154, v[118:121] offset:24576
	s_waitcnt vmcnt(3)
	ds_write_b128 v186, v[122:125] offset:32768
	s_waitcnt vmcnt(2)
	ds_write_b128 v186, v[126:129] offset:33792
	s_waitcnt vmcnt(1)
	ds_write_b128 v186, v[130:133] offset:34816
	s_waitcnt vmcnt(0)
	ds_write_b128 v186, v[134:137] offset:35840
	s_waitcnt lgkmcnt(0)
	s_barrier
	v_mfma_f32_32x32x16_bf16 v[0:15], v[216:219], v[206:209], v[0:15]
	s_cbranch_vccnz .LBB0_386
	s_add_u32 s94, s94, 0xb9000
	s_addc_u32 s95, s95, 0
	global_load_dwordx4 v[114:117], v176, s[94:95]
	global_load_dwordx4 v[118:121], v177, s[94:95]
	global_load_dwordx4 v[122:125], v178, s[94:95]
	global_load_dwordx4 v[126:129], v179, s[94:95]
	global_load_dwordx4 v[130:133], v180, s[94:95]
	global_load_dwordx4 v[134:137], v181, s[94:95]
; #define MFMA(a, b, c) __builtin_amdgcn_mfma_f32_32x32x16_bf16((a), (b), (c), 0, 0, 0)
; DI int crow(int reg, int h) { return (reg & 3) + 8 * (reg >> 2) + 4 * h; }
; DI float fexp2(float x) { return __builtin_amdgcn_exp2f(x); }
; DI float mx2(float a, float b) { return __builtin_elementwise_maximum(a, b); }
; DI float hmax(float v) { auto rr = __builtin_amdgcn_permlane32_swap(__float_as_uint(v), __float_as_uint(v), false, false); return mx2(__uint_as_float(rr[0]), __uint_as_float(rr[1])); }
; template <int DV>
; DI void attn_core(const u16* __restrict__ P, size_t tokbase, int kcol, int vcol, int n1, int n2, int xs0,
;                   bool win, int tq, float m0, float l0, f32x16 (&o)[DV / 32], float& lsum, char* lds) {
;     ...
;     for (int ks = 0; ks < 2; ++ks) {
;       f32x16 pt = negm;
; #pragma unroll
;       for (int s = 0; s < 4; ++s) {
;         const int ch = 2 * s + h, key = 32 * ks + r;
;         const bf16x8 kf = *(const bf16x8*)(base + ch * 1024 + ((key ^ ch) * 16));
;         const bf16x8 qf = qreg[s];
;         pt = MFMA(kf, qf, pt);
;       }
;       if (domask) {
; #pragma unroll
;         for (int reg = 0; reg < 16; ++reg) {
;           const int d = tq - (kt0 + 32 * ks + crow(reg, h));
;           if (d > 128 || d < -128) pt[reg] = -1e30f;
;         }
;       }
;       float mloc = mx2(pt[0], pt[1]);
; #pragma unroll
;       for (int reg = 2; reg < 16; reg += 2) mloc = mx2(mx2(mloc, pt[reg]), pt[reg + 1]);
;       mloc = hmax(mloc);
;       const bool first = autoinit && it == 0 && ks == 0;
;       if (first || __builtin_amdgcn_ballot_w64(mloc > THR) != 0) {
;         const float d = first ? mloc : fmaxf(mloc, 0.f);
;         const float alpha = fexp2(-d);
;         m += d; l *= alpha;
; #pragma unroll
;         for (int reg = 0; reg < 16; ++reg) { negm[reg] = -m; pt[reg] -= d; }
; #pragma unroll
;         for (int b = 0; b < DV / 32; ++b)
; #pragma unroll
;           for (int reg = 0; reg < 16; ++reg) o[b][reg] *= alpha;
;       }
;       float la = 0.f;
; #pragma unroll
;       for (int reg = 0; reg < 16; ++reg) { const float e = fexp2(pt[reg]); pt[reg] = e; la += e; }
;       l += la;
.LBB0_386:
	v_add_f32_e32 v82, 0, v82
	v_add_f32_e32 v82, v83, v82
	v_add_f32_e32 v82, v84, v82
	v_add_f32_e32 v82, v85, v82
	v_add_f32_e32 v82, v86, v82
	v_add_f32_e32 v82, v87, v82
	v_add_f32_e32 v82, v88, v82
	v_add_f32_e32 v82, v89, v82
	ds_read_b128 v[206:209], v168 offset:24576
	v_add_f32_e32 v82, v90, v82
	v_add_f32_e32 v82, v91, v82
	v_add_f32_e32 v82, v92, v82
	v_add_f32_e32 v82, v93, v82
	v_add_f32_e32 v82, v94, v82
	v_add_f32_e32 v82, v95, v82
	v_add_f32_e32 v82, v96, v82
	v_add_f32_e32 v82, v97, v82
	v_add_f32_e32 v144, v187, v82
	s_waitcnt lgkmcnt(0)
	v_mfma_f32_32x32x16_bf16 v[82:97], v[206:209], v[98:101], v[66:81]
	ds_read_b128 v[206:209], v174 offset:24576
	s_waitcnt lgkmcnt(0)
	v_mfma_f32_32x32x16_bf16 v[82:97], v[206:209], v[102:105], v[82:97]
	ds_read_b128 v[206:209], v182 offset:24576
	s_waitcnt lgkmcnt(0)
	v_mfma_f32_32x32x16_bf16 v[82:97], v[206:209], v[106:109], v[82:97]
	ds_read_b128 v[206:209], v185 offset:24576
	s_waitcnt lgkmcnt(0)
	v_mfma_f32_32x32x16_bf16 v[82:97], v[206:209], v[110:113], v[82:97]
	s_nop 11
	v_maximum3_f32 v145, v82, v83, v83
	v_maximum3_f32 v145, v145, v84, v85
	v_maximum3_f32 v145, v145, v86, v87
	v_maximum3_f32 v145, v145, v88, v89
	v_maximum3_f32 v145, v145, v90, v91
	v_maximum3_f32 v145, v145, v92, v93
	v_maximum3_f32 v145, v145, v94, v95
	v_maximum3_f32 v145, v145, v96, v97
	v_mov_b32_e32 v146, v145
	s_nop 1
	v_permlane32_swap_b32_e32 v145, v146
	v_maximum3_f32 v145, v145, v146, v146
	v_cmp_lt_f32_e32 vcc, s80, v145
	s_cbranch_vccz .LBB0_388
	v_max_f32_e32 v66, v145, v145
	v_max_f32_e32 v68, 0, v66
	v_exp_f32_e64 v70, -v68
	v_add_f32_e32 v166, v166, v68
	v_xor_b32_e32 v66, 0x80000000, v166
	v_pk_add_f32 v[82:83], v[82:83], v[68:69] op_sel_hi:[1,0] neg_lo:[0,1] neg_hi:[0,1]
	v_mul_f32_e32 v144, v144, v70
	v_pk_add_f32 v[84:85], v[84:85], v[68:69] op_sel_hi:[1,0] neg_lo:[0,1] neg_hi:[0,1]
	v_pk_add_f32 v[86:87], v[86:87], v[68:69] op_sel_hi:[1,0] neg_lo:[0,1] neg_hi:[0,1]
	v_pk_add_f32 v[88:89], v[88:89], v[68:69] op_sel_hi:[1,0] neg_lo:[0,1] neg_hi:[0,1]
	v_pk_add_f32 v[90:91], v[90:91], v[68:69] op_sel_hi:[1,0] neg_lo:[0,1] neg_hi:[0,1]
	v_pk_add_f32 v[92:93], v[92:93], v[68:69] op_sel_hi:[1,0] neg_lo:[0,1] neg_hi:[0,1]
	v_pk_add_f32 v[94:95], v[94:95], v[68:69] op_sel_hi:[1,0] neg_lo:[0,1] neg_hi:[0,1]
	v_pk_add_f32 v[96:97], v[96:97], v[68:69] op_sel_hi:[1,0] neg_lo:[0,1] neg_hi:[0,1]
	v_pk_mul_f32 v[62:63], v[62:63], v[70:71] op_sel_hi:[1,0]
	v_pk_mul_f32 v[60:61], v[60:61], v[70:71] op_sel_hi:[1,0]
	v_pk_mul_f32 v[58:59], v[58:59], v[70:71] op_sel_hi:[1,0]
	v_pk_mul_f32 v[56:57], v[56:57], v[70:71] op_sel_hi:[1,0]
	v_pk_mul_f32 v[54:55], v[54:55], v[70:71] op_sel_hi:[1,0]
	v_pk_mul_f32 v[52:53], v[52:53], v[70:71] op_sel_hi:[1,0]
	v_pk_mul_f32 v[50:51], v[50:51], v[70:71] op_sel_hi:[1,0]
	v_pk_mul_f32 v[48:49], v[48:49], v[70:71] op_sel_hi:[1,0]
	v_pk_mul_f32 v[46:47], v[46:47], v[70:71] op_sel_hi:[1,0]
	v_pk_mul_f32 v[44:45], v[44:45], v[70:71] op_sel_hi:[1,0]
	v_pk_mul_f32 v[42:43], v[42:43], v[70:71] op_sel_hi:[1,0]
	v_pk_mul_f32 v[40:41], v[40:41], v[70:71] op_sel_hi:[1,0]
	v_pk_mul_f32 v[38:39], v[38:39], v[70:71] op_sel_hi:[1,0]
	v_pk_mul_f32 v[36:37], v[36:37], v[70:71] op_sel_hi:[1,0]
	v_pk_mul_f32 v[34:35], v[34:35], v[70:71] op_sel_hi:[1,0]
	v_pk_mul_f32 v[32:33], v[32:33], v[70:71] op_sel_hi:[1,0]
	v_pk_mul_f32 v[30:31], v[30:31], v[70:71] op_sel_hi:[1,0]
	v_pk_mul_f32 v[28:29], v[28:29], v[70:71] op_sel_hi:[1,0]
	v_pk_mul_f32 v[26:27], v[26:27], v[70:71] op_sel_hi:[1,0]
	v_pk_mul_f32 v[24:25], v[24:25], v[70:71] op_sel_hi:[1,0]
	v_pk_mul_f32 v[22:23], v[22:23], v[70:71] op_sel_hi:[1,0]
	v_pk_mul_f32 v[20:21], v[20:21], v[70:71] op_sel_hi:[1,0]
	v_pk_mul_f32 v[18:19], v[18:19], v[70:71] op_sel_hi:[1,0]
	v_pk_mul_f32 v[16:17], v[16:17], v[70:71] op_sel_hi:[1,0]
	v_pk_mul_f32 v[14:15], v[14:15], v[70:71] op_sel_hi:[1,0]
	v_pk_mul_f32 v[12:13], v[12:13], v[70:71] op_sel_hi:[1,0]
	v_pk_mul_f32 v[10:11], v[10:11], v[70:71] op_sel_hi:[1,0]
	v_pk_mul_f32 v[8:9], v[8:9], v[70:71] op_sel_hi:[1,0]
	v_pk_mul_f32 v[6:7], v[6:7], v[70:71] op_sel_hi:[1,0]
	v_pk_mul_f32 v[4:5], v[4:5], v[70:71] op_sel_hi:[1,0]
	v_pk_mul_f32 v[2:3], v[2:3], v[70:71] op_sel_hi:[1,0]
	v_pk_mul_f32 v[0:1], v[0:1], v[70:71] op_sel_hi:[1,0]
	v_mov_b32_e32 v67, v66
	v_mov_b32_e32 v68, v66
	v_mov_b32_e32 v69, v66
	v_mov_b32_e32 v70, v66
	v_mov_b32_e32 v71, v66
	v_mov_b32_e32 v72, v66
	v_mov_b32_e32 v73, v66
	v_mov_b32_e32 v74, v66
	v_mov_b32_e32 v75, v66
	v_mov_b32_e32 v76, v66
	v_mov_b32_e32 v77, v66
	v_mov_b32_e32 v78, v66
	v_mov_b32_e32 v79, v66
	v_mov_b32_e32 v80, v66
	v_mov_b32_e32 v81, v66
	v_mov_b32_e32 v148, v66
	v_mov_b32_e32 v167, v66
	v_mov_b32_e32 v169, v66
	v_mov_b32_e32 v170, v66
	v_mov_b32_e32 v171, v66
	v_mov_b32_e32 v172, v66
	v_mov_b32_e32 v173, v66
	v_mov_b32_e32 v175, v66
	v_mov_b32_e32 v183, v66
	v_mov_b32_e32 v184, v66
